# c9 + the safe-softmax (mfix>40) G==256 attention path also reads the relocated V^T (consistency fix for p34_merge; path checked by forcing it in a side build)
# baseline (speedup 1.0000x reference)
; #define LAS __attribute__((address_space(3)))
; #define ATT_LOADG(t) do { kA = *(const u32x4*)(Kh + (size_t)(t) * 6144 + tid * 8); if (tid < 256) kB = *(const u32x4*)(Kh + (size_t)(t) * 6144 + c2 * 8); \
;         vA = *(const u32x4*)(Vh + (size_t)vr * T + 64 * (t) + vc * 8); } while (0)
; #define ATT_STORE(buf) do { *(LAS u32x4*)(Kb + (buf) * 6656 + kr1 * 104 + kc1 * 8) = kA; if (tid < 256) *(LAS u32x4*)(Kb + (buf) * 6656 + kr2 * 104 + kc2 * 8) = kB; \
;         *(LAS u32x2*)(Vb + (buf) * 4352 + vr * 68 + vc * 8) = (u32x2){vA[0], vA[1]}; *(LAS u32x2*)(Vb + (buf) * 4352 + vr * 68 + vc * 8 + 4) = (u32x2){vA[2], vA[3]}; } while (0)
; #define ATT_LOADG(t) do { kA = *(const u32x4*)(Kh + (size_t)(t) * 6144 + tid * 8); if (tid < 256) kB = *(const u32x4*)(Kh + (size_t)(t) * 6144 + c2 * 8); \
;         vA = *(const u32x4*)(Vh + (size_t)vr * T + 64 * (t) + vc * 8); } while (0)
; template <bool FIX> __device__ __forceinline__ void attn_unit(const bf16_t* Q, const bf16_t* K, const bf16_t* Vt, bf16_t* O, int bh, int qb, float mfix, LAS unsigned char* lds) {
;     const int tid = threadIdx.x, lane = tid & 63, wid = __builtin_amdgcn_readfirstlane(tid >> 6), r = lane & 31, hh = lane >> 5;
;     LAS bf16_t* Kb = (LAS bf16_t*)lds;
;     LAS bf16_t* Vb = (LAS bf16_t*)(lds + 2 * 64 * 104 * 2);
;     const bf16_t* Qh = Q + (size_t)bh * SEQ * 96; const bf16_t* Kh = K + (size_t)bh * SEQ * 96; const bf16_t* Vh = Vt + (size_t)(bh & 7) * 64 * T + (size_t)(bh >> 3) * SEQ;
;     const int q0 = qb * 256, qw = q0 + wid * 32, NTL = 4 * (qb + 1);
;     bf16x8 qf[6];
; #pragma unroll
;     for (int d0 = 0; d0 < 6; ++d0) qf[d0] = *(const bf16x8*)(Qh + (size_t)(qw + r) * 96 + 16 * d0 + 8 * hh);
;     f32x16 o0, o1;
; #pragma unroll
;     for (int i = 0; i < 16; ++i) { o0[i] = 0.f; o1[i] = 0.f; }
;     float mrun = -1e30f, lrun = 0.f;
;     f32x16 cinit;
; #pragma unroll
;     for (int i = 0; i < 16; ++i) cinit[i] = FIX ? -mfix : 0.f;
;     asm volatile("" : "+v"(cinit));
;     const int c2 = 512 + tid, kr1 = tid / 12, kc1 = tid % 12, kr2 = c2 / 12, kc2 = c2 % 12, vr = tid >> 3, vc = tid & 7;
;     u32x4 kA, kB = {0u, 0u, 0u, 0u}, vA;
;     ...
;     ATT_LOADG(0); ATT_STORE(0); __syncthreads();
.LBB0_757:
	s_andn2_b64 vcc, exec, s[16:17]
	s_cbranch_vccnz .LBB0_785
	v_or_b32_e32 v1, v201, v194
	v_lshlrev_b32_e32 v167, 2, v1
	v_or_b32_e32 v1, v201, v172
	v_lshlrev_b32_e32 v211, 2, v1
	v_or_b32_e32 v1, v201, v173
	v_lshlrev_b32_e32 v212, 2, v1
	v_or_b32_e32 v1, v201, v174
	v_lshlrev_b32_e32 v213, 2, v1
	v_or_b32_e32 v1, v201, v175
	v_lshlrev_b32_e32 v214, 2, v1
	v_or_b32_e32 v1, v201, v176
	v_lshlrev_b32_e32 v215, 2, v1
	v_or_b32_e32 v1, v201, v177
	v_lshlrev_b32_e32 v216, 2, v1
	v_or_b32_e32 v1, v201, v178
	v_mul_u32_u24_e32 v0, 0x88, v195
	v_lshlrev_b32_e32 v217, 2, v1
	v_or_b32_e32 v1, v201, v179
	v_add3_u32 v166, 0, v199, v0
	v_mov_b32_e32 v0, 0
	v_lshlrev_b32_e32 v218, 2, v1
	v_or_b32_e32 v1, v201, v180
	s_or_b32 s18, s42, 8
	s_xor_b32 s19, s42, 15
	v_lshlrev_b32_e32 v2, 1, v195
	v_mov_b32_e32 v3, v0
	v_lshlrev_b32_e32 v219, 2, v1
	v_or_b32_e32 v1, v201, v181
	v_lshl_add_u64 v[158:159], s[10:11], 0, v[2:3]
	v_lshlrev_b32_e32 v220, 2, v1
	v_or_b32_e32 v1, v201, v182
	s_add_u32 s10, s50, s58
	v_lshlrev_b32_e32 v221, 2, v1
	v_or_b32_e32 v1, v201, v183
	v_mov_b32_e32 v157, v0
	s_addc_u32 s11, s51, s57
	v_lshlrev_b32_e32 v223, 2, v1
	v_or_b32_e32 v1, v201, v184
	v_lshl_add_u64 v[2:3], s[10:11], 0, v[156:157]
	s_mov_b64 s[10:11], 0x4003000
	v_lshlrev_b32_e32 v224, 2, v1
	v_or_b32_e32 v1, v201, v185
	v_lshl_add_u64 v[156:157], v[2:3], 0, s[10:11]
	s_lshl_b32 s10, s2, 20
	v_lshlrev_b32_e32 v225, 2, v1
	v_or_b32_e32 v1, v201, v200
	s_and_b32 s10, s10, 0x1c00000
	v_lshlrev_b32_e32 v201, 2, v1
	v_lshlrev_b32_e32 v1, 13, v254
	s_add_u32 s8, s8, s10
	v_and_b32_e32 v2, 0x7f0000, v1
	v_mov_b32_e32 v3, v0
	s_addc_u32 s9, s9, 0
	v_and_b32_e32 v1, 7, v254
	v_lshl_add_u64 v[2:3], s[8:9], 0, v[2:3]
	v_lshlrev_b32_e32 v4, 4, v1
	v_mov_b32_e32 v5, v0
	v_lshl_add_u64 v[2:3], v[2:3], 0, v[4:5]
	s_add_u32 s8, s59, 0x80
	s_addc_u32 s9, s60, 0
	s_mov_b32 s3, 0
	v_or_b32_e32 v168, 4, v167
	v_or_b32_e32 v169, 8, v167
	v_or_b32_e32 v170, 12, v167
	v_or_b32_e32 v171, 32, v167
	v_or_b32_e32 v198, 36, v167
	v_or_b32_e32 v199, 40, v167
	v_or_b32_e32 v202, 44, v167
	v_or_b32_e32 v203, 64, v167
	v_or_b32_e32 v204, 0x44, v167
	v_or_b32_e32 v205, 0x48, v167
	v_or_b32_e32 v206, 0x4c, v167
	v_or_b32_e32 v207, 0x60, v167
	v_or_b32_e32 v208, 0x64, v167
	v_or_b32_e32 v209, 0x68, v167
	v_or_b32_e32 v210, 0x6c, v167
	v_lshl_add_u64 v[160:161], v[2:3], 0, s[8:9]
	s_movk_i32 s20, 0xc0
	s_mov_b64 s[8:9], 0x3000
	s_mov_b64 s[10:11], 0x80
	v_mov_b32_e32 v16, 0
	v_mov_b32_e32 v17, v0
	v_mov_b32_e32 v18, v0
	v_mov_b32_e32 v19, v0
	v_mov_b32_e32 v20, v0
	v_mov_b32_e32 v21, v0
	v_mov_b32_e32 v22, v0
	v_mov_b32_e32 v23, v0
	v_mov_b32_e32 v24, v0
	v_mov_b32_e32 v25, v0
	v_mov_b32_e32 v26, v0
	v_mov_b32_e32 v27, v0
	v_mov_b32_e32 v28, v0
	v_mov_b32_e32 v29, v0
	v_mov_b32_e32 v30, v0
	v_mov_b32_e32 v31, v0
	v_mov_b32_e32 v226, 0xf149f2ca
